# in-proj unit order: XCD-7 chunk rotated per list so padded-row/padded-token tiles (slow statistics epilogue) never close the critical rounds (both layers); plus previous stack
# speedup vs baseline: 1.0279x; 1.0052x over previous
.LBB0_89:
	s_lshl_b32 s4, s7, 3
	v_cvt_f32_u32_e32 v1, s4
	s_sub_i32 s7, 0, s4
	s_ashr_i32 s5, s45, 3
	s_add_i32 s5, s46, s5
	s_sub_i32 s45, s5, s46
	s_add_i32 s65, s45, s66
	s_add_i32 s65, s65, -9
	s_cmp_ge_i32 s65, s66
	s_cselect_b32 vcc_lo, s66, 0
	s_sub_i32 s65, s65, vcc_lo
	s_add_i32 vcc_hi, s66, 0xffffffe0
	s_add_i32 vcc_lo, s45, 0xffffffef
	s_cmp_ge_i32 vcc_lo, vcc_hi
	s_cselect_b32 vcc_hi, vcc_hi, 0
	s_sub_i32 vcc_lo, vcc_lo, vcc_hi
	s_add_i32 vcc_lo, vcc_lo, 32
	s_cmp_lt_i32 s45, 32
	s_cselect_b32 vcc_lo, s45, vcc_lo
	s_cmp_lt_i32 s66, 60
	s_cselect_b32 vcc_lo, s45, vcc_lo
	s_cmp_eq_u32 s63, 1
	s_cselect_b32 s65, s65, vcc_lo
	s_add_i32 s65, s65, s46
	s_cmp_eq_u32 s47, 7
	s_cselect_b32 s5, s65, s5
	v_rcp_iflag_f32_e32 v1, v1
	s_abs_i32 s46, s5
	s_ashr_i32 s45, s5, 31
	v_mul_f32_e32 v1, 0x4f7ffffe, v1
	v_cvt_u32_f32_e32 v1, v1
	s_nop 0
	v_readfirstlane_b32 s47, v1
	s_mul_i32 s7, s7, s47
	s_mul_hi_u32 s7, s47, s7
	s_add_i32 s47, s47, s7
	s_mul_hi_u32 s7, s46, s47
	s_mul_i32 s47, s7, s4
	s_sub_i32 s46, s46, s47
	s_add_i32 s65, s7, 1
	s_sub_i32 s47, s46, s4
	s_cmp_ge_u32 s46, s4
	s_cselect_b32 s7, s65, s7
	s_cselect_b32 s46, s47, s46
	s_add_i32 s47, s7, 1
	s_cmp_ge_u32 s46, s4
	s_cselect_b32 s7, s47, s7
	s_xor_b32 s7, s7, s45
	s_sub_i32 s7, s7, s45
	s_lshl_b32 s45, s7, 3
	s_sub_i32 s6, s6, s45
	s_min_i32 s6, s6, 8
	s_abs_i32 s46, s6
	v_cvt_f32_u32_e32 v1, s46
	s_sub_i32 s47, 0, s46
	s_mul_i32 s7, s7, s4
	s_sub_i32 s4, s5, s7
	v_rcp_iflag_f32_e32 v1, v1
	s_abs_i32 s5, s4
	s_xor_b32 s7, s4, s6
	s_ashr_i32 s7, s7, 31
	v_mul_f32_e32 v1, 0x4f7ffffe, v1
	v_cvt_u32_f32_e32 v1, v1
	s_nop 0
	v_readfirstlane_b32 s65, v1
	s_mul_i32 s47, s47, s65
	s_mul_hi_u32 s47, s65, s47
	s_add_i32 s65, s65, s47
	s_mul_hi_u32 s47, s5, s65
	s_mul_i32 s65, s47, s46
	s_sub_i32 s5, s5, s65
	s_add_i32 s66, s47, 1
	s_sub_i32 s65, s5, s46
	s_cmp_ge_u32 s5, s46
	s_cselect_b32 s47, s66, s47
	s_cselect_b32 s5, s65, s5
	s_add_i32 s65, s47, 1
	s_cmp_ge_u32 s5, s46
	s_cselect_b32 s5, s65, s47
	s_xor_b32 s5, s5, s7
	s_sub_i32 s94, s5, s7
	s_mul_i32 s5, s94, s6
	s_sub_i32 s4, s4, s5
	s_add_i32 s6, s4, s45
